# v36 + pro_xconv: prologue x->bf16 loop replaced by fully unrolled 6-chunk-deep software pipeline (counted vmcnt, saddr loads)
# speedup vs baseline: 1.0070x; 1.0020x over previous
; DI unsigned pk2(float lo, float hi) { const f32x2 v = {lo, hi}; const bf16x2_t b = __builtin_convertvector(v, bf16x2_t); return __builtin_bit_cast(unsigned, b); }
; DI void prologue(KA a, LAS unsigned char* lds) {
;     ...
;     { const float* x = a->in[I_X]; bf16* act = (bf16*)(ws + WS_ACT); const size_t stride = (size_t)gridDim.x * NTHR, n8 = (size_t)T * D / 8;
;       for (size_t i = (size_t)blockIdx.x * NTHR + tid; i < n8; i += 4 * stride) { f32x4 v0[4], v1[4];
; #pragma unroll
;           for (int u = 0; u < 4; ++u) { const size_t ii = i + u * stride; if (ii < n8) { v0[u] = *(const f32x4*)(x + ii * 8); v1[u] = *(const f32x4*)(x + ii * 8 + 4); } }
; #pragma unroll
;           for (int u = 0; u < 4; ++u) { const size_t ii = i + u * stride; if (ii < n8) { v4u o; o.x = pk2(v0[u][0], v0[u][1]); o.y = pk2(v0[u][2], v0[u][3]); o.z = pk2(v1[u][0], v1[u][1]); o.w = pk2(v1[u][2], v1[u][3]); *(v4u*)(act + ii * 8) = o; } } } }
.LBB0_197:
	s_or_b64 exec, exec, s[4:5]
	s_mov_b32 s75, 0
	s_lshl_b64 s[0:1], s[74:75], 9
	v_ashrrev_i32_e32 v21, 31, v20
	v_lshl_add_u64 v[50:51], s[0:1], 0, v[20:21]
	s_mov_b64 s[4:5], 0x400000
	v_cmp_gt_u64_e32 vcc, s[4:5], v[50:51]
	s_and_saveexec_b64 s[6:7], vcc
	s_cbranch_execz .LBB0_212
	s_load_dwordx2 s[8:9], s[28:29], 0x0
	v_lshlrev_b32_e32 v51, 4, v50
	v_lshlrev_b32_e32 v50, 5, v50
	s_add_u32 s10, s26, 0x4000000
	s_addc_u32 s11, s27, 0
	s_waitcnt lgkmcnt(0)
	global_load_dwordx4 v[2:5], v50, s[8:9]
	global_load_dwordx4 v[6:9], v50, s[8:9] offset:16
	s_add_u32 s8, s8, 0x400000
	s_addc_u32 s9, s9, 0
	global_load_dwordx4 v[10:13], v50, s[8:9]
	global_load_dwordx4 v[14:17], v50, s[8:9] offset:16
	s_add_u32 s8, s8, 0x400000
	s_addc_u32 s9, s9, 0
	global_load_dwordx4 v[18:21], v50, s[8:9]
	global_load_dwordx4 v[22:25], v50, s[8:9] offset:16
	s_add_u32 s8, s8, 0x400000
	s_addc_u32 s9, s9, 0
	global_load_dwordx4 v[26:29], v50, s[8:9]
	global_load_dwordx4 v[30:33], v50, s[8:9] offset:16
	s_add_u32 s8, s8, 0x400000
	s_addc_u32 s9, s9, 0
	global_load_dwordx4 v[34:37], v50, s[8:9]
	global_load_dwordx4 v[38:41], v50, s[8:9] offset:16
	s_add_u32 s8, s8, 0x400000
	s_addc_u32 s9, s9, 0
	global_load_dwordx4 v[42:45], v50, s[8:9]
	global_load_dwordx4 v[46:49], v50, s[8:9] offset:16
	s_add_u32 s8, s8, 0x400000
	s_addc_u32 s9, s9, 0
	s_waitcnt vmcnt(10)
	v_cvt_pk_bf16_f32 v2, v2, v3
	v_cvt_pk_bf16_f32 v3, v4, v5
	v_cvt_pk_bf16_f32 v4, v6, v7
	v_cvt_pk_bf16_f32 v5, v8, v9
	global_store_dwordx4 v51, v[2:5], s[10:11]
	s_add_u32 s10, s10, 0x200000
	s_addc_u32 s11, s11, 0
	global_load_dwordx4 v[2:5], v50, s[8:9]
	global_load_dwordx4 v[6:9], v50, s[8:9] offset:16
	s_add_u32 s8, s8, 0x400000
	s_addc_u32 s9, s9, 0
	s_waitcnt vmcnt(11)
	v_cvt_pk_bf16_f32 v10, v10, v11
	v_cvt_pk_bf16_f32 v11, v12, v13
	v_cvt_pk_bf16_f32 v12, v14, v15
	v_cvt_pk_bf16_f32 v13, v16, v17
	global_store_dwordx4 v51, v[10:13], s[10:11]
	s_add_u32 s10, s10, 0x200000
	s_addc_u32 s11, s11, 0
	global_load_dwordx4 v[10:13], v50, s[8:9]
	global_load_dwordx4 v[14:17], v50, s[8:9] offset:16
	s_add_u32 s8, s8, 0x400000
	s_addc_u32 s9, s9, 0
	s_waitcnt vmcnt(12)
	v_cvt_pk_bf16_f32 v18, v18, v19
	v_cvt_pk_bf16_f32 v19, v20, v21
	v_cvt_pk_bf16_f32 v20, v22, v23
	v_cvt_pk_bf16_f32 v21, v24, v25
	global_store_dwordx4 v51, v[18:21], s[10:11]
	s_add_u32 s10, s10, 0x200000
	s_addc_u32 s11, s11, 0
	global_load_dwordx4 v[18:21], v50, s[8:9]
	global_load_dwordx4 v[22:25], v50, s[8:9] offset:16
	s_add_u32 s8, s8, 0x400000
	s_addc_u32 s9, s9, 0
	s_waitcnt vmcnt(13)
	v_cvt_pk_bf16_f32 v26, v26, v27
	v_cvt_pk_bf16_f32 v27, v28, v29
	v_cvt_pk_bf16_f32 v28, v30, v31
	v_cvt_pk_bf16_f32 v29, v32, v33
	global_store_dwordx4 v51, v[26:29], s[10:11]
	s_add_u32 s10, s10, 0x200000
	s_addc_u32 s11, s11, 0
	global_load_dwordx4 v[26:29], v50, s[8:9]
	global_load_dwordx4 v[30:33], v50, s[8:9] offset:16
	s_add_u32 s8, s8, 0x400000
	s_addc_u32 s9, s9, 0
	s_waitcnt vmcnt(14)
	v_cvt_pk_bf16_f32 v34, v34, v35
	v_cvt_pk_bf16_f32 v35, v36, v37
	v_cvt_pk_bf16_f32 v36, v38, v39
	v_cvt_pk_bf16_f32 v37, v40, v41
	global_store_dwordx4 v51, v[34:37], s[10:11]
	s_add_u32 s10, s10, 0x200000
	s_addc_u32 s11, s11, 0
	global_load_dwordx4 v[34:37], v50, s[8:9]
	global_load_dwordx4 v[38:41], v50, s[8:9] offset:16
	s_add_u32 s8, s8, 0x400000
	s_addc_u32 s9, s9, 0
	s_waitcnt vmcnt(15)
	v_cvt_pk_bf16_f32 v42, v42, v43
	v_cvt_pk_bf16_f32 v43, v44, v45
	v_cvt_pk_bf16_f32 v44, v46, v47
	v_cvt_pk_bf16_f32 v45, v48, v49
	global_store_dwordx4 v51, v[42:45], s[10:11]
	s_add_u32 s10, s10, 0x200000
	s_addc_u32 s11, s11, 0
	global_load_dwordx4 v[42:45], v50, s[8:9]
	global_load_dwordx4 v[46:49], v50, s[8:9] offset:16
	s_add_u32 s8, s8, 0x400000
	s_addc_u32 s9, s9, 0
	s_waitcnt vmcnt(15)
	v_cvt_pk_bf16_f32 v2, v2, v3
	v_cvt_pk_bf16_f32 v3, v4, v5
	v_cvt_pk_bf16_f32 v4, v6, v7
	v_cvt_pk_bf16_f32 v5, v8, v9
	global_store_dwordx4 v51, v[2:5], s[10:11]
	s_add_u32 s10, s10, 0x200000
	s_addc_u32 s11, s11, 0
	global_load_dwordx4 v[2:5], v50, s[8:9]
	global_load_dwordx4 v[6:9], v50, s[8:9] offset:16
	s_add_u32 s8, s8, 0x400000
	s_addc_u32 s9, s9, 0
	s_waitcnt vmcnt(15)
	v_cvt_pk_bf16_f32 v10, v10, v11
	v_cvt_pk_bf16_f32 v11, v12, v13
	v_cvt_pk_bf16_f32 v12, v14, v15
	v_cvt_pk_bf16_f32 v13, v16, v17
	global_store_dwordx4 v51, v[10:13], s[10:11]
	s_add_u32 s10, s10, 0x200000
	s_addc_u32 s11, s11, 0
	global_load_dwordx4 v[10:13], v50, s[8:9]
	global_load_dwordx4 v[14:17], v50, s[8:9] offset:16
	s_add_u32 s8, s8, 0x400000
	s_addc_u32 s9, s9, 0
	s_waitcnt vmcnt(15)
	v_cvt_pk_bf16_f32 v18, v18, v19
	v_cvt_pk_bf16_f32 v19, v20, v21
	v_cvt_pk_bf16_f32 v20, v22, v23
	v_cvt_pk_bf16_f32 v21, v24, v25
	global_store_dwordx4 v51, v[18:21], s[10:11]
	s_add_u32 s10, s10, 0x200000
	s_addc_u32 s11, s11, 0
	global_load_dwordx4 v[18:21], v50, s[8:9]
	global_load_dwordx4 v[22:25], v50, s[8:9] offset:16
	s_add_u32 s8, s8, 0x400000
	s_addc_u32 s9, s9, 0
	s_waitcnt vmcnt(15)
	v_cvt_pk_bf16_f32 v26, v26, v27
	v_cvt_pk_bf16_f32 v27, v28, v29
	v_cvt_pk_bf16_f32 v28, v30, v31
	v_cvt_pk_bf16_f32 v29, v32, v33
	global_store_dwordx4 v51, v[26:29], s[10:11]
	s_add_u32 s10, s10, 0x200000
	s_addc_u32 s11, s11, 0
	global_load_dwordx4 v[26:29], v50, s[8:9]
	global_load_dwordx4 v[30:33], v50, s[8:9] offset:16
	s_add_u32 s8, s8, 0x400000
	s_addc_u32 s9, s9, 0
	s_waitcnt vmcnt(15)
	v_cvt_pk_bf16_f32 v34, v34, v35
	v_cvt_pk_bf16_f32 v35, v36, v37
	v_cvt_pk_bf16_f32 v36, v38, v39
	v_cvt_pk_bf16_f32 v37, v40, v41
	global_store_dwordx4 v51, v[34:37], s[10:11]
	s_add_u32 s10, s10, 0x200000
	s_addc_u32 s11, s11, 0
	global_load_dwordx4 v[34:37], v50, s[8:9]
	global_load_dwordx4 v[38:41], v50, s[8:9] offset:16
	s_add_u32 s8, s8, 0x400000
	s_addc_u32 s9, s9, 0
	s_waitcnt vmcnt(15)
; DI unsigned pk2(float lo, float hi) { const f32x2 v = {lo, hi}; const bf16x2_t b = __builtin_convertvector(v, bf16x2_t); return __builtin_bit_cast(unsigned, b); }
; DI void prologue(KA a, LAS unsigned char* lds) {
;     ...
;     { const float* x = a->in[I_X]; bf16* act = (bf16*)(ws + WS_ACT); const size_t stride = (size_t)gridDim.x * NTHR, n8 = (size_t)T * D / 8;
;       for (size_t i = (size_t)blockIdx.x * NTHR + tid; i < n8; i += 4 * stride) { f32x4 v0[4], v1[4];
; #pragma unroll
;           for (int u = 0; u < 4; ++u) { const size_t ii = i + u * stride; if (ii < n8) { v0[u] = *(const f32x4*)(x + ii * 8); v1[u] = *(const f32x4*)(x + ii * 8 + 4); } }
; #pragma unroll
;           for (int u = 0; u < 4; ++u) { const size_t ii = i + u * stride; if (ii < n8) { v4u o; o.x = pk2(v0[u][0], v0[u][1]); o.y = pk2(v0[u][2], v0[u][3]); o.z = pk2(v1[u][0], v1[u][1]); o.w = pk2(v1[u][2], v1[u][3]); *(v4u*)(act + ii * 8) = o; } } } }
	v_cvt_pk_bf16_f32 v42, v42, v43
	v_cvt_pk_bf16_f32 v43, v44, v45
	v_cvt_pk_bf16_f32 v44, v46, v47
	v_cvt_pk_bf16_f32 v45, v48, v49
	global_store_dwordx4 v51, v[42:45], s[10:11]
	s_add_u32 s10, s10, 0x200000
	s_addc_u32 s11, s11, 0
	global_load_dwordx4 v[42:45], v50, s[8:9]
	global_load_dwordx4 v[46:49], v50, s[8:9] offset:16
	s_add_u32 s8, s8, 0x400000
	s_addc_u32 s9, s9, 0
	s_waitcnt vmcnt(15)
	v_cvt_pk_bf16_f32 v2, v2, v3
	v_cvt_pk_bf16_f32 v3, v4, v5
	v_cvt_pk_bf16_f32 v4, v6, v7
	v_cvt_pk_bf16_f32 v5, v8, v9
	global_store_dwordx4 v51, v[2:5], s[10:11]
	s_add_u32 s10, s10, 0x200000
	s_addc_u32 s11, s11, 0
	global_load_dwordx4 v[2:5], v50, s[8:9]
	global_load_dwordx4 v[6:9], v50, s[8:9] offset:16
	s_add_u32 s8, s8, 0x400000
	s_addc_u32 s9, s9, 0
	s_waitcnt vmcnt(15)
	v_cvt_pk_bf16_f32 v10, v10, v11
	v_cvt_pk_bf16_f32 v11, v12, v13
	v_cvt_pk_bf16_f32 v12, v14, v15
	v_cvt_pk_bf16_f32 v13, v16, v17
	global_store_dwordx4 v51, v[10:13], s[10:11]
	s_add_u32 s10, s10, 0x200000
	s_addc_u32 s11, s11, 0
	global_load_dwordx4 v[10:13], v50, s[8:9]
	global_load_dwordx4 v[14:17], v50, s[8:9] offset:16
	s_add_u32 s8, s8, 0x400000
	s_addc_u32 s9, s9, 0
	s_waitcnt vmcnt(15)
	v_cvt_pk_bf16_f32 v18, v18, v19
	v_cvt_pk_bf16_f32 v19, v20, v21
	v_cvt_pk_bf16_f32 v20, v22, v23
	v_cvt_pk_bf16_f32 v21, v24, v25
	global_store_dwordx4 v51, v[18:21], s[10:11]
	s_add_u32 s10, s10, 0x200000
	s_addc_u32 s11, s11, 0
	global_load_dwordx4 v[18:21], v50, s[8:9]
	global_load_dwordx4 v[22:25], v50, s[8:9] offset:16
	s_add_u32 s8, s8, 0x400000
	s_addc_u32 s9, s9, 0
	s_waitcnt vmcnt(15)
	v_cvt_pk_bf16_f32 v26, v26, v27
	v_cvt_pk_bf16_f32 v27, v28, v29
	v_cvt_pk_bf16_f32 v28, v30, v31
	v_cvt_pk_bf16_f32 v29, v32, v33
	global_store_dwordx4 v51, v[26:29], s[10:11]
	s_add_u32 s10, s10, 0x200000
	s_addc_u32 s11, s11, 0
	global_load_dwordx4 v[26:29], v50, s[8:9]
	global_load_dwordx4 v[30:33], v50, s[8:9] offset:16
	s_add_u32 s8, s8, 0x400000
	s_addc_u32 s9, s9, 0
	s_waitcnt vmcnt(15)
	v_cvt_pk_bf16_f32 v34, v34, v35
	v_cvt_pk_bf16_f32 v35, v36, v37
	v_cvt_pk_bf16_f32 v36, v38, v39
	v_cvt_pk_bf16_f32 v37, v40, v41
	global_store_dwordx4 v51, v[34:37], s[10:11]
	s_add_u32 s10, s10, 0x200000
	s_addc_u32 s11, s11, 0
	global_load_dwordx4 v[34:37], v50, s[8:9]
	global_load_dwordx4 v[38:41], v50, s[8:9] offset:16
	s_add_u32 s8, s8, 0x400000
	s_addc_u32 s9, s9, 0
	s_waitcnt vmcnt(15)
	v_cvt_pk_bf16_f32 v42, v42, v43
	v_cvt_pk_bf16_f32 v43, v44, v45
	v_cvt_pk_bf16_f32 v44, v46, v47
	v_cvt_pk_bf16_f32 v45, v48, v49
	global_store_dwordx4 v51, v[42:45], s[10:11]
	s_add_u32 s10, s10, 0x200000
	s_addc_u32 s11, s11, 0
	global_load_dwordx4 v[42:45], v50, s[8:9]
	global_load_dwordx4 v[46:49], v50, s[8:9] offset:16
	s_add_u32 s8, s8, 0x400000
	s_addc_u32 s9, s9, 0
	s_waitcnt vmcnt(15)
	v_cvt_pk_bf16_f32 v2, v2, v3
	v_cvt_pk_bf16_f32 v3, v4, v5
	v_cvt_pk_bf16_f32 v4, v6, v7
	v_cvt_pk_bf16_f32 v5, v8, v9
	global_store_dwordx4 v51, v[2:5], s[10:11]
	s_add_u32 s10, s10, 0x200000
	s_addc_u32 s11, s11, 0
	global_load_dwordx4 v[2:5], v50, s[8:9]
	global_load_dwordx4 v[6:9], v50, s[8:9] offset:16
	s_add_u32 s8, s8, 0x400000
	s_addc_u32 s9, s9, 0
	s_waitcnt vmcnt(15)
	v_cvt_pk_bf16_f32 v10, v10, v11
	v_cvt_pk_bf16_f32 v11, v12, v13
	v_cvt_pk_bf16_f32 v12, v14, v15
	v_cvt_pk_bf16_f32 v13, v16, v17
	global_store_dwordx4 v51, v[10:13], s[10:11]
	s_add_u32 s10, s10, 0x200000
	s_addc_u32 s11, s11, 0
	global_load_dwordx4 v[10:13], v50, s[8:9]
	global_load_dwordx4 v[14:17], v50, s[8:9] offset:16
	s_add_u32 s8, s8, 0x400000
	s_addc_u32 s9, s9, 0
	s_waitcnt vmcnt(15)
; DI unsigned pk2(float lo, float hi) { const f32x2 v = {lo, hi}; const bf16x2_t b = __builtin_convertvector(v, bf16x2_t); return __builtin_bit_cast(unsigned, b); }
; DI void prologue(KA a, LAS unsigned char* lds) {
;     ...
;     { const float* x = a->in[I_X]; bf16* act = (bf16*)(ws + WS_ACT); const size_t stride = (size_t)gridDim.x * NTHR, n8 = (size_t)T * D / 8;
;       for (size_t i = (size_t)blockIdx.x * NTHR + tid; i < n8; i += 4 * stride) { f32x4 v0[4], v1[4];
; #pragma unroll
;           for (int u = 0; u < 4; ++u) { const size_t ii = i + u * stride; if (ii < n8) { v0[u] = *(const f32x4*)(x + ii * 8); v1[u] = *(const f32x4*)(x + ii * 8 + 4); } }
; #pragma unroll
;           for (int u = 0; u < 4; ++u) { const size_t ii = i + u * stride; if (ii < n8) { v4u o; o.x = pk2(v0[u][0], v0[u][1]); o.y = pk2(v0[u][2], v0[u][3]); o.z = pk2(v1[u][0], v1[u][1]); o.w = pk2(v1[u][2], v1[u][3]); *(v4u*)(act + ii * 8) = o; } } } }
	v_cvt_pk_bf16_f32 v18, v18, v19
	v_cvt_pk_bf16_f32 v19, v20, v21
	v_cvt_pk_bf16_f32 v20, v22, v23
	v_cvt_pk_bf16_f32 v21, v24, v25
	global_store_dwordx4 v51, v[18:21], s[10:11]
	s_add_u32 s10, s10, 0x200000
	s_addc_u32 s11, s11, 0
	global_load_dwordx4 v[18:21], v50, s[8:9]
	global_load_dwordx4 v[22:25], v50, s[8:9] offset:16
	s_add_u32 s8, s8, 0x400000
	s_addc_u32 s9, s9, 0
	s_waitcnt vmcnt(15)
	v_cvt_pk_bf16_f32 v26, v26, v27
	v_cvt_pk_bf16_f32 v27, v28, v29
	v_cvt_pk_bf16_f32 v28, v30, v31
	v_cvt_pk_bf16_f32 v29, v32, v33
	global_store_dwordx4 v51, v[26:29], s[10:11]
	s_add_u32 s10, s10, 0x200000
	s_addc_u32 s11, s11, 0
	global_load_dwordx4 v[26:29], v50, s[8:9]
	global_load_dwordx4 v[30:33], v50, s[8:9] offset:16
	s_add_u32 s8, s8, 0x400000
	s_addc_u32 s9, s9, 0
	s_waitcnt vmcnt(15)
	v_cvt_pk_bf16_f32 v34, v34, v35
	v_cvt_pk_bf16_f32 v35, v36, v37
	v_cvt_pk_bf16_f32 v36, v38, v39
	v_cvt_pk_bf16_f32 v37, v40, v41
	global_store_dwordx4 v51, v[34:37], s[10:11]
	s_add_u32 s10, s10, 0x200000
	s_addc_u32 s11, s11, 0
	global_load_dwordx4 v[34:37], v50, s[8:9]
	global_load_dwordx4 v[38:41], v50, s[8:9] offset:16
	s_add_u32 s8, s8, 0x400000
	s_addc_u32 s9, s9, 0
	s_waitcnt vmcnt(15)
	v_cvt_pk_bf16_f32 v42, v42, v43
	v_cvt_pk_bf16_f32 v43, v44, v45
	v_cvt_pk_bf16_f32 v44, v46, v47
	v_cvt_pk_bf16_f32 v45, v48, v49
	global_store_dwordx4 v51, v[42:45], s[10:11]
	s_add_u32 s10, s10, 0x200000
	s_addc_u32 s11, s11, 0
	global_load_dwordx4 v[42:45], v50, s[8:9]
	global_load_dwordx4 v[46:49], v50, s[8:9] offset:16
	s_add_u32 s8, s8, 0x400000
	s_addc_u32 s9, s9, 0
	s_waitcnt vmcnt(15)
	v_cvt_pk_bf16_f32 v2, v2, v3
	v_cvt_pk_bf16_f32 v3, v4, v5
	v_cvt_pk_bf16_f32 v4, v6, v7
	v_cvt_pk_bf16_f32 v5, v8, v9
	global_store_dwordx4 v51, v[2:5], s[10:11]
	s_add_u32 s10, s10, 0x200000
	s_addc_u32 s11, s11, 0
	global_load_dwordx4 v[2:5], v50, s[8:9]
	global_load_dwordx4 v[6:9], v50, s[8:9] offset:16
	s_add_u32 s8, s8, 0x400000
	s_addc_u32 s9, s9, 0
	s_waitcnt vmcnt(15)
	v_cvt_pk_bf16_f32 v10, v10, v11
	v_cvt_pk_bf16_f32 v11, v12, v13
	v_cvt_pk_bf16_f32 v12, v14, v15
	v_cvt_pk_bf16_f32 v13, v16, v17
	global_store_dwordx4 v51, v[10:13], s[10:11]
	s_add_u32 s10, s10, 0x200000
	s_addc_u32 s11, s11, 0
	global_load_dwordx4 v[10:13], v50, s[8:9]
	global_load_dwordx4 v[14:17], v50, s[8:9] offset:16
	s_waitcnt vmcnt(15)
	v_cvt_pk_bf16_f32 v18, v18, v19
	v_cvt_pk_bf16_f32 v19, v20, v21
	v_cvt_pk_bf16_f32 v20, v22, v23
	v_cvt_pk_bf16_f32 v21, v24, v25
	global_store_dwordx4 v51, v[18:21], s[10:11]
	s_add_u32 s10, s10, 0x200000
	s_addc_u32 s11, s11, 0
	s_waitcnt vmcnt(13)
	v_cvt_pk_bf16_f32 v26, v26, v27
	v_cvt_pk_bf16_f32 v27, v28, v29
	v_cvt_pk_bf16_f32 v28, v30, v31
	v_cvt_pk_bf16_f32 v29, v32, v33
	global_store_dwordx4 v51, v[26:29], s[10:11]
	s_add_u32 s10, s10, 0x200000
	s_addc_u32 s11, s11, 0
	s_waitcnt vmcnt(11)
	v_cvt_pk_bf16_f32 v34, v34, v35
	v_cvt_pk_bf16_f32 v35, v36, v37
	v_cvt_pk_bf16_f32 v36, v38, v39
	v_cvt_pk_bf16_f32 v37, v40, v41
	global_store_dwordx4 v51, v[34:37], s[10:11]
	s_add_u32 s10, s10, 0x200000
	s_addc_u32 s11, s11, 0
	s_waitcnt vmcnt(9)
	v_cvt_pk_bf16_f32 v42, v42, v43
	v_cvt_pk_bf16_f32 v43, v44, v45
	v_cvt_pk_bf16_f32 v44, v46, v47
	v_cvt_pk_bf16_f32 v45, v48, v49
	global_store_dwordx4 v51, v[42:45], s[10:11]
	s_add_u32 s10, s10, 0x200000
	s_addc_u32 s11, s11, 0
	s_waitcnt vmcnt(7)
	v_cvt_pk_bf16_f32 v2, v2, v3
	v_cvt_pk_bf16_f32 v3, v4, v5
	v_cvt_pk_bf16_f32 v4, v6, v7
	v_cvt_pk_bf16_f32 v5, v8, v9
	global_store_dwordx4 v51, v[2:5], s[10:11]
	s_add_u32 s10, s10, 0x200000
	s_addc_u32 s11, s11, 0
	s_waitcnt vmcnt(5)
	v_cvt_pk_bf16_f32 v10, v10, v11
	v_cvt_pk_bf16_f32 v11, v12, v13
	v_cvt_pk_bf16_f32 v12, v14, v15
	v_cvt_pk_bf16_f32 v13, v16, v17
	global_store_dwordx4 v51, v[10:13], s[10:11]
	s_waitcnt vmcnt(0)
